# v125 plus epilogue-head waits relaxed from vmcnt(0) to vmcnt(8) at the four GEMM epilogue heads
# baseline (speedup 1.0000x reference)
; __device__ __forceinline__ unsigned cvt_pk_bf16(float lo, float hi) { unsigned r; asm volatile("v_cvt_pk_bf16_f32 %0, %1, %2" : "=v"(r) : "v"(lo), "v"(hi)); return r; }
; __device__ __forceinline__ float silu_mul(float g, float u) {
;     const float e = __builtin_amdgcn_exp2f(g * -1.4426950408889634f);
;     return g * __builtin_amdgcn_rcpf(1.0f + e) * u;
; }
;     __device__ __forceinline__ void operator()(const f32x4 (&acc)[2][2][4][2], const Unit& u, int wr, int wc, int fr, int fq, const float (&rv)[8]) const {
;         const int row0 = u.pm * BM + wr * 64 + fr, col0 = u.pn * HALF + wc * 32 + 8 * fq;
; #pragma unroll
;         for (int ai = 0; ai < 2; ++ai)
; #pragma unroll
;             for (int m = 0; m < 4; ++m) {
;                 bf16_t* rowp = O + (size_t)(row0 + ai * HALF + m * 16) * ldc + col0;
;                 const float r = rv[ai * 4 + m];
;                 const f32x4 g0 = acc[ai][0][m][0] * r, g1 = acc[ai][0][m][1] * r, u0 = acc[ai][1][m][0] * r, u1 = acc[ai][1][m][1] * r;
;                 u32x4 w;
;                 w.x = cvt_pk_bf16(silu_mul(g0[0], u0[0]), silu_mul(g0[1], u0[1]));
;                 w.y = cvt_pk_bf16(silu_mul(g0[2], u0[2]), silu_mul(g0[3], u0[3]));
;                 w.z = cvt_pk_bf16(silu_mul(g1[0], u1[0]), silu_mul(g1[1], u1[1]));
;                 w.w = cvt_pk_bf16(silu_mul(g1[2], u1[2]), silu_mul(g1[3], u1[3]));
;                 *(u32x4*)rowp = w;
.LBB0_105:
	s_waitcnt vmcnt(8)
	s_mov_b32 s98, 0xbfb8aa3b
	s_mov_b32 s99, 0xbfb8aa3b
	s_mov_b32 s100, 1.0
	s_mov_b32 s101, 1.0
	s_nop 7
	s_nop 7
	v_pk_mul_f32 v[124:125], v[158:159], v[124:125] op_sel_hi:[0,1]
	v_pk_mul_f32 v[116:117], v[158:159], v[116:117] op_sel_hi:[0,1]
	v_pk_mul_f32 v[126:127], v[158:159], v[126:127] op_sel_hi:[0,1]
	v_pk_mul_f32 v[118:119], v[158:159], v[118:119] op_sel_hi:[0,1]
	v_pk_mul_f32 v[246:247], v[124:125], s[98:99]
	v_pk_mul_f32 v[248:249], v[126:127], s[98:99]
	v_exp_f32_e32 v246, v246
	v_exp_f32_e32 v247, v247
	v_exp_f32_e32 v248, v248
	v_exp_f32_e32 v249, v249
	v_pk_add_f32 v[246:247], v[246:247], s[100:101]
	v_pk_add_f32 v[248:249], v[248:249], s[100:101]
	v_rcp_f32_e32 v246, v246
	v_rcp_f32_e32 v247, v247
	v_rcp_f32_e32 v248, v248
	v_rcp_f32_e32 v249, v249
	v_pk_mul_f32 v[124:125], v[124:125], v[246:247]
	v_pk_mul_f32 v[126:127], v[126:127], v[248:249]
	v_pk_mul_f32 v[124:125], v[124:125], v[116:117]
	v_pk_mul_f32 v[126:127], v[126:127], v[118:119]
	v_lshl_or_b32 v162, s87, 7, v153
	v_lshl_add_u32 v164, s4, 8, v137
	v_ashrrev_i32_e32 v163, 31, v162
	v_mov_b64_e32 v[160:161], s[14:15]
	v_mad_i64_i32 v[166:167], s[10:11], v164, s86, v[160:161]
	v_lshlrev_b64 v[162:163], 1, v[162:163]
	v_lshl_add_u64 v[166:167], v[166:167], 0, v[162:163]
	v_pk_mul_f32 v[120:121], v[158:159], v[120:121] op_sel_hi:[0,1]
	v_pk_mul_f32 v[112:113], v[158:159], v[112:113] op_sel_hi:[0,1]
	v_pk_mul_f32 v[122:123], v[158:159], v[122:123] op_sel_hi:[0,1]
	v_pk_mul_f32 v[114:115], v[158:159], v[114:115] op_sel_hi:[0,1]
	v_pk_mul_f32 v[246:247], v[120:121], s[98:99]
	v_pk_mul_f32 v[248:249], v[122:123], s[98:99]
	v_exp_f32_e32 v246, v246
	v_exp_f32_e32 v247, v247
	v_exp_f32_e32 v248, v248
	v_exp_f32_e32 v249, v249
	v_pk_add_f32 v[246:247], v[246:247], s[100:101]
	v_pk_add_f32 v[248:249], v[248:249], s[100:101]
	v_rcp_f32_e32 v246, v246
	v_rcp_f32_e32 v247, v247
	v_rcp_f32_e32 v248, v248
	v_rcp_f32_e32 v249, v249
	v_pk_mul_f32 v[120:121], v[120:121], v[246:247]
	v_pk_mul_f32 v[122:123], v[122:123], v[248:249]
	v_pk_mul_f32 v[120:121], v[120:121], v[112:113]
	v_pk_mul_f32 v[122:123], v[122:123], v[114:115]
	v_cvt_pk_bf16_f32 v112, v124, v125
	v_cvt_pk_bf16_f32 v113, v126, v127
	v_cvt_pk_bf16_f32 v114, v120, v121
	v_cvt_pk_bf16_f32 v115, v122, v123
	global_store_dwordx4 v[166:167], v[112:115], off
	v_pk_mul_f32 v[108:109], v[156:157], v[108:109] op_sel_hi:[0,1]
	v_pk_mul_f32 v[100:101], v[156:157], v[100:101] op_sel_hi:[0,1]
	v_pk_mul_f32 v[110:111], v[156:157], v[110:111] op_sel_hi:[0,1]
	v_pk_mul_f32 v[102:103], v[156:157], v[102:103] op_sel_hi:[0,1]
	v_pk_mul_f32 v[246:247], v[108:109], s[98:99]
	v_pk_mul_f32 v[248:249], v[110:111], s[98:99]
	v_exp_f32_e32 v246, v246
	v_exp_f32_e32 v247, v247
	v_exp_f32_e32 v248, v248
	v_exp_f32_e32 v249, v249
	v_pk_add_f32 v[246:247], v[246:247], s[100:101]
	v_pk_add_f32 v[248:249], v[248:249], s[100:101]
	v_rcp_f32_e32 v246, v246
	v_rcp_f32_e32 v247, v247
	v_rcp_f32_e32 v248, v248
	v_rcp_f32_e32 v249, v249
	v_pk_mul_f32 v[108:109], v[108:109], v[246:247]
	v_pk_mul_f32 v[110:111], v[110:111], v[248:249]
	v_pk_mul_f32 v[108:109], v[108:109], v[100:101]
	v_pk_mul_f32 v[110:111], v[110:111], v[102:103]
	v_or_b32_e32 v112, 16, v164
	v_mad_i64_i32 v[112:113], s[10:11], v112, s86, v[160:161]
	v_lshl_add_u64 v[112:113], v[112:113], 0, v[162:163]
	v_pk_mul_f32 v[104:105], v[156:157], v[104:105] op_sel_hi:[0,1]
	v_pk_mul_f32 v[96:97], v[156:157], v[96:97] op_sel_hi:[0,1]
	v_pk_mul_f32 v[106:107], v[156:157], v[106:107] op_sel_hi:[0,1]
	v_pk_mul_f32 v[98:99], v[156:157], v[98:99] op_sel_hi:[0,1]
	v_pk_mul_f32 v[246:247], v[104:105], s[98:99]
	v_pk_mul_f32 v[248:249], v[106:107], s[98:99]
	v_exp_f32_e32 v246, v246
	v_exp_f32_e32 v247, v247
	v_exp_f32_e32 v248, v248
	v_exp_f32_e32 v249, v249
	v_pk_add_f32 v[246:247], v[246:247], s[100:101]
	v_pk_add_f32 v[248:249], v[248:249], s[100:101]
	v_rcp_f32_e32 v246, v246
	v_rcp_f32_e32 v247, v247
	v_rcp_f32_e32 v248, v248
	v_rcp_f32_e32 v249, v249
	v_pk_mul_f32 v[104:105], v[104:105], v[246:247]
	v_pk_mul_f32 v[106:107], v[106:107], v[248:249]
	v_pk_mul_f32 v[104:105], v[104:105], v[96:97]
	v_pk_mul_f32 v[106:107], v[106:107], v[98:99]
	v_cvt_pk_bf16_f32 v96, v108, v109
	v_cvt_pk_bf16_f32 v97, v110, v111
	v_cvt_pk_bf16_f32 v98, v104, v105
	v_cvt_pk_bf16_f32 v99, v106, v107
	global_store_dwordx4 v[112:113], v[96:99], off
	v_pk_mul_f32 v[92:93], v[154:155], v[92:93] op_sel_hi:[0,1]
	v_pk_mul_f32 v[84:85], v[154:155], v[84:85] op_sel_hi:[0,1]
	v_pk_mul_f32 v[94:95], v[154:155], v[94:95] op_sel_hi:[0,1]
	v_pk_mul_f32 v[86:87], v[154:155], v[86:87] op_sel_hi:[0,1]
	v_pk_mul_f32 v[246:247], v[92:93], s[98:99]
	v_pk_mul_f32 v[248:249], v[94:95], s[98:99]
	v_exp_f32_e32 v246, v246
	v_exp_f32_e32 v247, v247
	v_exp_f32_e32 v248, v248
	v_exp_f32_e32 v249, v249
	v_pk_add_f32 v[246:247], v[246:247], s[100:101]
	v_pk_add_f32 v[248:249], v[248:249], s[100:101]
	v_rcp_f32_e32 v246, v246
	v_rcp_f32_e32 v247, v247
	v_rcp_f32_e32 v248, v248
	v_rcp_f32_e32 v249, v249
	v_pk_mul_f32 v[92:93], v[92:93], v[246:247]
	v_pk_mul_f32 v[94:95], v[94:95], v[248:249]
	v_pk_mul_f32 v[92:93], v[92:93], v[84:85]
	v_pk_mul_f32 v[94:95], v[94:95], v[86:87]
	v_or_b32_e32 v96, 32, v164
	v_mad_i64_i32 v[96:97], s[10:11], v96, s86, v[160:161]
	v_lshl_add_u64 v[96:97], v[96:97], 0, v[162:163]
	v_pk_mul_f32 v[88:89], v[154:155], v[88:89] op_sel_hi:[0,1]
	v_pk_mul_f32 v[80:81], v[154:155], v[80:81] op_sel_hi:[0,1]
	v_pk_mul_f32 v[90:91], v[154:155], v[90:91] op_sel_hi:[0,1]
	v_pk_mul_f32 v[82:83], v[154:155], v[82:83] op_sel_hi:[0,1]
	v_pk_mul_f32 v[246:247], v[88:89], s[98:99]
	v_pk_mul_f32 v[248:249], v[90:91], s[98:99]
; __device__ __forceinline__ unsigned cvt_pk_bf16(float lo, float hi) { unsigned r; asm volatile("v_cvt_pk_bf16_f32 %0, %1, %2" : "=v"(r) : "v"(lo), "v"(hi)); return r; }
; __device__ __forceinline__ float silu_mul(float g, float u) {
;     const float e = __builtin_amdgcn_exp2f(g * -1.4426950408889634f);
;     return g * __builtin_amdgcn_rcpf(1.0f + e) * u;
; }
;     __device__ __forceinline__ void operator()(const f32x4 (&acc)[2][2][4][2], const Unit& u, int wr, int wc, int fr, int fq, const float (&rv)[8]) const {
;         const int row0 = u.pm * BM + wr * 64 + fr, col0 = u.pn * HALF + wc * 32 + 8 * fq;
; #pragma unroll
;         for (int ai = 0; ai < 2; ++ai)
; #pragma unroll
;             for (int m = 0; m < 4; ++m) {
;                 bf16_t* rowp = O + (size_t)(row0 + ai * HALF + m * 16) * ldc + col0;
;                 const float r = rv[ai * 4 + m];
;                 const f32x4 g0 = acc[ai][0][m][0] * r, g1 = acc[ai][0][m][1] * r, u0 = acc[ai][1][m][0] * r, u1 = acc[ai][1][m][1] * r;
;                 u32x4 w;
;                 w.x = cvt_pk_bf16(silu_mul(g0[0], u0[0]), silu_mul(g0[1], u0[1]));
;                 w.y = cvt_pk_bf16(silu_mul(g0[2], u0[2]), silu_mul(g0[3], u0[3]));
;                 w.z = cvt_pk_bf16(silu_mul(g1[0], u1[0]), silu_mul(g1[1], u1[1]));
;                 w.w = cvt_pk_bf16(silu_mul(g1[2], u1[2]), silu_mul(g1[3], u1[3]));
;                 *(u32x4*)rowp = w;
	v_exp_f32_e32 v246, v246
	v_exp_f32_e32 v247, v247
	v_exp_f32_e32 v248, v248
	v_exp_f32_e32 v249, v249
	v_pk_add_f32 v[246:247], v[246:247], s[100:101]
	v_pk_add_f32 v[248:249], v[248:249], s[100:101]
	v_rcp_f32_e32 v246, v246
	v_rcp_f32_e32 v247, v247
	v_rcp_f32_e32 v248, v248
	v_rcp_f32_e32 v249, v249
	v_pk_mul_f32 v[88:89], v[88:89], v[246:247]
	v_pk_mul_f32 v[90:91], v[90:91], v[248:249]
	v_pk_mul_f32 v[88:89], v[88:89], v[80:81]
	v_pk_mul_f32 v[90:91], v[90:91], v[82:83]
	v_cvt_pk_bf16_f32 v80, v92, v93
	v_cvt_pk_bf16_f32 v81, v94, v95
	v_cvt_pk_bf16_f32 v82, v88, v89
	v_cvt_pk_bf16_f32 v83, v90, v91
	global_store_dwordx4 v[96:97], v[80:83], off
	v_pk_mul_f32 v[76:77], v[152:153], v[76:77] op_sel_hi:[0,1]
	v_pk_mul_f32 v[68:69], v[152:153], v[68:69] op_sel_hi:[0,1]
	v_pk_mul_f32 v[78:79], v[152:153], v[78:79] op_sel_hi:[0,1]
	v_pk_mul_f32 v[70:71], v[152:153], v[70:71] op_sel_hi:[0,1]
	v_pk_mul_f32 v[246:247], v[76:77], s[98:99]
	v_pk_mul_f32 v[248:249], v[78:79], s[98:99]
	v_exp_f32_e32 v246, v246
	v_exp_f32_e32 v247, v247
	v_exp_f32_e32 v248, v248
	v_exp_f32_e32 v249, v249
	v_pk_add_f32 v[246:247], v[246:247], s[100:101]
	v_pk_add_f32 v[248:249], v[248:249], s[100:101]
	v_rcp_f32_e32 v246, v246
	v_rcp_f32_e32 v247, v247
	v_rcp_f32_e32 v248, v248
	v_rcp_f32_e32 v249, v249
	v_pk_mul_f32 v[76:77], v[76:77], v[246:247]
	v_pk_mul_f32 v[78:79], v[78:79], v[248:249]
	v_pk_mul_f32 v[76:77], v[76:77], v[68:69]
	v_pk_mul_f32 v[78:79], v[78:79], v[70:71]
	v_or_b32_e32 v80, 48, v164
	v_mad_i64_i32 v[80:81], s[10:11], v80, s86, v[160:161]
	v_lshl_add_u64 v[80:81], v[80:81], 0, v[162:163]
	v_pk_mul_f32 v[72:73], v[152:153], v[72:73] op_sel_hi:[0,1]
	v_pk_mul_f32 v[64:65], v[152:153], v[64:65] op_sel_hi:[0,1]
	v_pk_mul_f32 v[74:75], v[152:153], v[74:75] op_sel_hi:[0,1]
	v_pk_mul_f32 v[66:67], v[152:153], v[66:67] op_sel_hi:[0,1]
	v_pk_mul_f32 v[246:247], v[72:73], s[98:99]
	v_pk_mul_f32 v[248:249], v[74:75], s[98:99]
	v_exp_f32_e32 v246, v246
	v_exp_f32_e32 v247, v247
	v_exp_f32_e32 v248, v248
	v_exp_f32_e32 v249, v249
	v_pk_add_f32 v[246:247], v[246:247], s[100:101]
	v_pk_add_f32 v[248:249], v[248:249], s[100:101]
	v_rcp_f32_e32 v246, v246
	v_rcp_f32_e32 v247, v247
	v_rcp_f32_e32 v248, v248
	v_rcp_f32_e32 v249, v249
	v_pk_mul_f32 v[72:73], v[72:73], v[246:247]
	v_pk_mul_f32 v[74:75], v[74:75], v[248:249]
	v_pk_mul_f32 v[72:73], v[72:73], v[64:65]
	v_pk_mul_f32 v[74:75], v[74:75], v[66:67]
	v_cvt_pk_bf16_f32 v64, v76, v77
	v_cvt_pk_bf16_f32 v65, v78, v79
	v_cvt_pk_bf16_f32 v66, v72, v73
	v_cvt_pk_bf16_f32 v67, v74, v75
	global_store_dwordx4 v[80:81], v[64:67], off
	v_pk_mul_f32 v[60:61], v[150:151], v[60:61] op_sel_hi:[0,1]
	v_pk_mul_f32 v[52:53], v[150:151], v[52:53] op_sel_hi:[0,1]
	v_pk_mul_f32 v[62:63], v[150:151], v[62:63] op_sel_hi:[0,1]
	v_pk_mul_f32 v[54:55], v[150:151], v[54:55] op_sel_hi:[0,1]
	v_pk_mul_f32 v[246:247], v[60:61], s[98:99]
	v_pk_mul_f32 v[248:249], v[62:63], s[98:99]
	v_exp_f32_e32 v246, v246
	v_exp_f32_e32 v247, v247
	v_exp_f32_e32 v248, v248
	v_exp_f32_e32 v249, v249
	v_pk_add_f32 v[246:247], v[246:247], s[100:101]
	v_pk_add_f32 v[248:249], v[248:249], s[100:101]
	v_rcp_f32_e32 v246, v246
	v_rcp_f32_e32 v247, v247
	v_rcp_f32_e32 v248, v248
	v_rcp_f32_e32 v249, v249
	v_pk_mul_f32 v[60:61], v[60:61], v[246:247]
	v_pk_mul_f32 v[62:63], v[62:63], v[248:249]
	v_pk_mul_f32 v[60:61], v[60:61], v[52:53]
	v_pk_mul_f32 v[62:63], v[62:63], v[54:55]
	v_add_u32_e32 v64, 0x80, v164
	v_mad_i64_i32 v[64:65], s[10:11], v64, s86, v[160:161]
	v_lshl_add_u64 v[64:65], v[64:65], 0, v[162:163]
	v_pk_mul_f32 v[56:57], v[150:151], v[56:57] op_sel_hi:[0,1]
	v_pk_mul_f32 v[48:49], v[150:151], v[48:49] op_sel_hi:[0,1]
	v_pk_mul_f32 v[58:59], v[150:151], v[58:59] op_sel_hi:[0,1]
	v_pk_mul_f32 v[50:51], v[150:151], v[50:51] op_sel_hi:[0,1]
	v_pk_mul_f32 v[246:247], v[56:57], s[98:99]
	v_pk_mul_f32 v[248:249], v[58:59], s[98:99]
	v_exp_f32_e32 v246, v246
	v_exp_f32_e32 v247, v247
	v_exp_f32_e32 v248, v248
	v_exp_f32_e32 v249, v249
	v_pk_add_f32 v[246:247], v[246:247], s[100:101]
	v_pk_add_f32 v[248:249], v[248:249], s[100:101]
	v_rcp_f32_e32 v246, v246
	v_rcp_f32_e32 v247, v247
	v_rcp_f32_e32 v248, v248
	v_rcp_f32_e32 v249, v249
	v_pk_mul_f32 v[56:57], v[56:57], v[246:247]
	v_pk_mul_f32 v[58:59], v[58:59], v[248:249]
	v_pk_mul_f32 v[56:57], v[56:57], v[48:49]
	v_pk_mul_f32 v[58:59], v[58:59], v[50:51]
	v_cvt_pk_bf16_f32 v48, v60, v61
	v_cvt_pk_bf16_f32 v49, v62, v63
	v_cvt_pk_bf16_f32 v50, v56, v57
	v_cvt_pk_bf16_f32 v51, v58, v59
	global_store_dwordx4 v[64:65], v[48:51], off
	v_pk_mul_f32 v[44:45], v[148:149], v[44:45] op_sel_hi:[0,1]
	v_pk_mul_f32 v[36:37], v[148:149], v[36:37] op_sel_hi:[0,1]
	v_pk_mul_f32 v[46:47], v[148:149], v[46:47] op_sel_hi:[0,1]
	v_pk_mul_f32 v[38:39], v[148:149], v[38:39] op_sel_hi:[0,1]
	v_pk_mul_f32 v[246:247], v[44:45], s[98:99]
	v_pk_mul_f32 v[248:249], v[46:47], s[98:99]
	v_exp_f32_e32 v246, v246
	v_exp_f32_e32 v247, v247
	v_exp_f32_e32 v248, v248
	v_exp_f32_e32 v249, v249
	v_pk_add_f32 v[246:247], v[246:247], s[100:101]
	v_pk_add_f32 v[248:249], v[248:249], s[100:101]
	v_rcp_f32_e32 v246, v246
	v_rcp_f32_e32 v247, v247
	v_rcp_f32_e32 v248, v248
	v_rcp_f32_e32 v249, v249
	v_pk_mul_f32 v[44:45], v[44:45], v[246:247]
	v_pk_mul_f32 v[46:47], v[46:47], v[248:249]
	v_pk_mul_f32 v[44:45], v[44:45], v[36:37]
	v_pk_mul_f32 v[46:47], v[46:47], v[38:39]
	v_add_u32_e32 v48, 0x90, v164
	v_mad_i64_i32 v[48:49], s[10:11], v48, s86, v[160:161]
	v_lshl_add_u64 v[48:49], v[48:49], 0, v[162:163]
; __device__ __forceinline__ unsigned cvt_pk_bf16(float lo, float hi) { unsigned r; asm volatile("v_cvt_pk_bf16_f32 %0, %1, %2" : "=v"(r) : "v"(lo), "v"(hi)); return r; }
; #define PG8_BAR __builtin_amdgcn_s_barrier()
;     __device__ __forceinline__ void operator()(const f32x4 (&acc)[2][2][4][2], const Unit& u, int wr, int wc, int fr, int fq, const float (&rv)[8]) const {
;     ...
;             for (int m = 0; m < 4; ++m) {
;                 bf16_t* rowp = O + (size_t)(row0 + ai * HALF + m * 16) * ldc + col0;
;                 const float r = rv[ai * 4 + m];
;                 const f32x4 g0 = acc[ai][0][m][0] * r, g1 = acc[ai][0][m][1] * r, u0 = acc[ai][1][m][0] * r, u1 = acc[ai][1][m][1] * r;
;                 u32x4 w;
;                 w.x = cvt_pk_bf16(silu_mul(g0[0], u0[0]), silu_mul(g0[1], u0[1]));
;                 w.y = cvt_pk_bf16(silu_mul(g0[2], u0[2]), silu_mul(g0[3], u0[3]));
;                 w.z = cvt_pk_bf16(silu_mul(g1[0], u1[0]), silu_mul(g1[1], u1[1]));
;                 w.w = cvt_pk_bf16(silu_mul(g1[2], u1[2]), silu_mul(g1[3], u1[3]));
;                 *(u32x4*)rowp = w;
; template <class Epi, class Sched, bool ALIGN_EPI = false, bool SP2 = false>
; __device__ __forceinline__ void gemm_phase(PG8_LAS unsigned char* lds, const Gemm g, const Sched& S, const Epi& E) {
;     ...
;         cur = nxt; cA = nA; cB = nB; ++ui;
;         E.pre(cur, wr, fr, epre);
;         if constexpr (ALIGN_EPI) { if (wr == 1) PG8_BAR; }
	v_pk_mul_f32 v[40:41], v[148:149], v[40:41] op_sel_hi:[0,1]
	v_pk_mul_f32 v[32:33], v[148:149], v[32:33] op_sel_hi:[0,1]
	v_pk_mul_f32 v[42:43], v[148:149], v[42:43] op_sel_hi:[0,1]
	v_pk_mul_f32 v[34:35], v[148:149], v[34:35] op_sel_hi:[0,1]
	v_pk_mul_f32 v[246:247], v[40:41], s[98:99]
	v_pk_mul_f32 v[248:249], v[42:43], s[98:99]
	v_exp_f32_e32 v246, v246
	v_exp_f32_e32 v247, v247
	v_exp_f32_e32 v248, v248
	v_exp_f32_e32 v249, v249
	v_pk_add_f32 v[246:247], v[246:247], s[100:101]
	v_pk_add_f32 v[248:249], v[248:249], s[100:101]
	v_rcp_f32_e32 v246, v246
	v_rcp_f32_e32 v247, v247
	v_rcp_f32_e32 v248, v248
	v_rcp_f32_e32 v249, v249
	v_pk_mul_f32 v[40:41], v[40:41], v[246:247]
	v_pk_mul_f32 v[42:43], v[42:43], v[248:249]
	v_pk_mul_f32 v[40:41], v[40:41], v[32:33]
	v_pk_mul_f32 v[42:43], v[42:43], v[34:35]
	v_cvt_pk_bf16_f32 v32, v44, v45
	v_cvt_pk_bf16_f32 v33, v46, v47
	v_cvt_pk_bf16_f32 v34, v40, v41
	v_cvt_pk_bf16_f32 v35, v42, v43
	global_store_dwordx4 v[48:49], v[32:35], off
	v_pk_mul_f32 v[28:29], v[146:147], v[28:29] op_sel_hi:[0,1]
	v_pk_mul_f32 v[20:21], v[146:147], v[20:21] op_sel_hi:[0,1]
	v_pk_mul_f32 v[30:31], v[146:147], v[30:31] op_sel_hi:[0,1]
	v_pk_mul_f32 v[22:23], v[146:147], v[22:23] op_sel_hi:[0,1]
	v_pk_mul_f32 v[246:247], v[28:29], s[98:99]
	v_pk_mul_f32 v[248:249], v[30:31], s[98:99]
	v_exp_f32_e32 v246, v246
	v_exp_f32_e32 v247, v247
	v_exp_f32_e32 v248, v248
	v_exp_f32_e32 v249, v249
	v_pk_add_f32 v[246:247], v[246:247], s[100:101]
	v_pk_add_f32 v[248:249], v[248:249], s[100:101]
	v_rcp_f32_e32 v246, v246
	v_rcp_f32_e32 v247, v247
	v_rcp_f32_e32 v248, v248
	v_rcp_f32_e32 v249, v249
	v_pk_mul_f32 v[28:29], v[28:29], v[246:247]
	v_pk_mul_f32 v[30:31], v[30:31], v[248:249]
	v_pk_mul_f32 v[28:29], v[28:29], v[20:21]
	v_pk_mul_f32 v[30:31], v[30:31], v[22:23]
	v_add_u32_e32 v32, 0xa0, v164
	v_mad_i64_i32 v[32:33], s[10:11], v32, s86, v[160:161]
	v_lshl_add_u64 v[32:33], v[32:33], 0, v[162:163]
	v_pk_mul_f32 v[24:25], v[146:147], v[24:25] op_sel_hi:[0,1]
	v_pk_mul_f32 v[16:17], v[146:147], v[16:17] op_sel_hi:[0,1]
	v_pk_mul_f32 v[26:27], v[146:147], v[26:27] op_sel_hi:[0,1]
	v_pk_mul_f32 v[18:19], v[146:147], v[18:19] op_sel_hi:[0,1]
	v_pk_mul_f32 v[246:247], v[24:25], s[98:99]
	v_pk_mul_f32 v[248:249], v[26:27], s[98:99]
	v_exp_f32_e32 v246, v246
	v_exp_f32_e32 v247, v247
	v_exp_f32_e32 v248, v248
	v_exp_f32_e32 v249, v249
	v_pk_add_f32 v[246:247], v[246:247], s[100:101]
	v_pk_add_f32 v[248:249], v[248:249], s[100:101]
	v_rcp_f32_e32 v246, v246
	v_rcp_f32_e32 v247, v247
	v_rcp_f32_e32 v248, v248
	v_rcp_f32_e32 v249, v249
	v_pk_mul_f32 v[24:25], v[24:25], v[246:247]
	v_pk_mul_f32 v[26:27], v[26:27], v[248:249]
	v_pk_mul_f32 v[24:25], v[24:25], v[16:17]
	v_pk_mul_f32 v[26:27], v[26:27], v[18:19]
	v_cvt_pk_bf16_f32 v16, v28, v29
	v_cvt_pk_bf16_f32 v17, v30, v31
	v_cvt_pk_bf16_f32 v18, v24, v25
	v_cvt_pk_bf16_f32 v19, v26, v27
	global_store_dwordx4 v[32:33], v[16:19], off
	v_pk_mul_f32 v[12:13], v[136:137], v[12:13] op_sel_hi:[0,1]
	v_pk_mul_f32 v[4:5], v[136:137], v[4:5] op_sel_hi:[0,1]
	v_pk_mul_f32 v[14:15], v[136:137], v[14:15] op_sel_hi:[0,1]
	v_pk_mul_f32 v[6:7], v[136:137], v[6:7] op_sel_hi:[0,1]
	v_pk_mul_f32 v[246:247], v[12:13], s[98:99]
	v_pk_mul_f32 v[248:249], v[14:15], s[98:99]
	v_exp_f32_e32 v246, v246
	v_exp_f32_e32 v247, v247
	v_exp_f32_e32 v248, v248
	v_exp_f32_e32 v249, v249
	v_pk_add_f32 v[246:247], v[246:247], s[100:101]
	v_pk_add_f32 v[248:249], v[248:249], s[100:101]
	v_rcp_f32_e32 v246, v246
	v_rcp_f32_e32 v247, v247
	v_rcp_f32_e32 v248, v248
	v_rcp_f32_e32 v249, v249
	v_pk_mul_f32 v[12:13], v[12:13], v[246:247]
	v_pk_mul_f32 v[14:15], v[14:15], v[248:249]
	v_pk_mul_f32 v[12:13], v[12:13], v[4:5]
	v_pk_mul_f32 v[14:15], v[14:15], v[6:7]
	v_add_u32_e32 v16, 0xb0, v164
	v_mad_i64_i32 v[16:17], s[10:11], v16, s86, v[160:161]
	v_lshl_add_u64 v[16:17], v[16:17], 0, v[162:163]
	s_andn2_b64 vcc, exec, s[0:1]
	s_mov_b64 s[0:1], -1
	v_pk_mul_f32 v[8:9], v[136:137], v[8:9] op_sel_hi:[0,1]
	v_pk_mul_f32 v[0:1], v[136:137], v[0:1] op_sel_hi:[0,1]
	v_pk_mul_f32 v[10:11], v[136:137], v[10:11] op_sel_hi:[0,1]
	v_pk_mul_f32 v[2:3], v[136:137], v[2:3] op_sel_hi:[0,1]
	v_pk_mul_f32 v[246:247], v[8:9], s[98:99]
	v_pk_mul_f32 v[248:249], v[10:11], s[98:99]
	v_exp_f32_e32 v246, v246
	v_exp_f32_e32 v247, v247
	v_exp_f32_e32 v248, v248
	v_exp_f32_e32 v249, v249
	v_pk_add_f32 v[246:247], v[246:247], s[100:101]
	v_pk_add_f32 v[248:249], v[248:249], s[100:101]
	v_rcp_f32_e32 v246, v246
	v_rcp_f32_e32 v247, v247
	v_rcp_f32_e32 v248, v248
	v_rcp_f32_e32 v249, v249
	v_pk_mul_f32 v[8:9], v[8:9], v[246:247]
	v_pk_mul_f32 v[10:11], v[10:11], v[248:249]
	v_pk_mul_f32 v[8:9], v[8:9], v[0:1]
	v_pk_mul_f32 v[10:11], v[10:11], v[2:3]
	v_cvt_pk_bf16_f32 v0, v12, v13
	v_cvt_pk_bf16_f32 v1, v14, v15
	v_cvt_pk_bf16_f32 v2, v8, v9
	v_cvt_pk_bf16_f32 v3, v10, v11
	global_store_dwordx4 v[16:17], v[0:3], off
	s_cbranch_vccnz .LBB0_98
	s_nop 0
	v_lshl_add_u32 v0, s54, 8, v137
	v_ashrrev_i32_e32 v1, 31, v0
	v_lshl_add_u64 v[0:1], v[0:1], 2, s[16:17]
	global_load_dword v158, v[0:1], off
	global_load_dword v156, v[0:1], off offset:64
	global_load_dword v154, v[0:1], off offset:128
	global_load_dword v152, v[0:1], off offset:192
	global_load_dword v150, v[0:1], off offset:512
	global_load_dword v148, v[0:1], off offset:576
	global_load_dword v146, v[0:1], off offset:640
	global_load_dword v136, v[0:1], off offset:704
	s_andn2_b64 vcc, exec, s[6:7]
	s_cbranch_vccnz .LBB0_97
	s_barrier
	s_branch .LBB0_97

; __device__ __forceinline__ unsigned cvt_pk_bf16(float lo, float hi) { unsigned r; asm volatile("v_cvt_pk_bf16_f32 %0, %1, %2" : "=v"(r) : "v"(lo), "v"(hi)); return r; }
;     __device__ __forceinline__ void operator()(const f32x4 (&acc)[2][2][4][2], const Unit& u, int wr, int wc, int fr, int fq, const float (&rv)[8]) const {
;         const int row0 = u.pm * BM + wr * 64 + fr, col0 = u.pn * HALF + wc * 32 + 8 * fq;
; #pragma unroll
;         for (int ai = 0; ai < 2; ++ai)
; #pragma unroll
;             for (int m = 0; m < 4; ++m) {
;                 bf16_t* rowp = O + (size_t)(row0 + ai * HALF + m * 16) * ldc + col0;
;                 const float r = rv[ai * 4 + m];
;                 const f32x4 g0 = acc[ai][0][m][0] * r, g1 = acc[ai][0][m][1] * r, u0 = acc[ai][1][m][0] * r, u1 = acc[ai][1][m][1] * r;
;                 u32x4 w;
;                 w.x = cvt_pk_bf16(silu_mul(g0[0], u0[0]), silu_mul(g0[1], u0[1]));
;                 w.y = cvt_pk_bf16(silu_mul(g0[2], u0[2]), silu_mul(g0[3], u0[3]));
;                 w.z = cvt_pk_bf16(silu_mul(g1[0], u1[0]), silu_mul(g1[1], u1[1]));
;                 w.w = cvt_pk_bf16(silu_mul(g1[2], u1[2]), silu_mul(g1[3], u1[3]));
;                 *(u32x4*)rowp = w;
.LBB0_703:
	s_waitcnt vmcnt(8)
	s_mov_b32 s98, 0xbfb8aa3b
	s_mov_b32 s99, 0xbfb8aa3b
	s_mov_b32 s100, 1.0
	s_mov_b32 s101, 1.0
	s_nop 7
	s_nop 7
	v_pk_mul_f32 v[124:125], v[162:163], v[124:125] op_sel_hi:[0,1]
	v_pk_mul_f32 v[116:117], v[162:163], v[116:117] op_sel_hi:[0,1]
	v_pk_mul_f32 v[126:127], v[162:163], v[126:127] op_sel_hi:[0,1]
	v_pk_mul_f32 v[118:119], v[162:163], v[118:119] op_sel_hi:[0,1]
	v_pk_mul_f32 v[246:247], v[124:125], s[98:99]
	v_pk_mul_f32 v[248:249], v[126:127], s[98:99]
	v_exp_f32_e32 v246, v246
	v_exp_f32_e32 v247, v247
	v_exp_f32_e32 v248, v248
	v_exp_f32_e32 v249, v249
	v_pk_add_f32 v[246:247], v[246:247], s[100:101]
	v_pk_add_f32 v[248:249], v[248:249], s[100:101]
	v_rcp_f32_e32 v246, v246
	v_rcp_f32_e32 v247, v247
	v_rcp_f32_e32 v248, v248
	v_rcp_f32_e32 v249, v249
	v_pk_mul_f32 v[124:125], v[124:125], v[246:247]
	v_pk_mul_f32 v[126:127], v[126:127], v[248:249]
	v_pk_mul_f32 v[124:125], v[124:125], v[116:117]
	v_pk_mul_f32 v[126:127], v[126:127], v[118:119]
	v_lshl_or_b32 v166, s64, 7, v153
	v_lshl_add_u32 v161, s42, 8, v137
	v_ashrrev_i32_e32 v167, 31, v166
	v_mov_b64_e32 v[164:165], s[14:15]
	v_mad_i64_i32 v[168:169], s[10:11], v161, s61, v[164:165]
	v_lshlrev_b64 v[166:167], 1, v[166:167]
	v_lshl_add_u64 v[168:169], v[168:169], 0, v[166:167]
	v_pk_mul_f32 v[120:121], v[162:163], v[120:121] op_sel_hi:[0,1]
	v_pk_mul_f32 v[112:113], v[162:163], v[112:113] op_sel_hi:[0,1]
	v_pk_mul_f32 v[122:123], v[162:163], v[122:123] op_sel_hi:[0,1]
	v_pk_mul_f32 v[114:115], v[162:163], v[114:115] op_sel_hi:[0,1]
	v_pk_mul_f32 v[246:247], v[120:121], s[98:99]
	v_pk_mul_f32 v[248:249], v[122:123], s[98:99]
	v_exp_f32_e32 v246, v246
	v_exp_f32_e32 v247, v247
	v_exp_f32_e32 v248, v248
	v_exp_f32_e32 v249, v249
	v_pk_add_f32 v[246:247], v[246:247], s[100:101]
	v_pk_add_f32 v[248:249], v[248:249], s[100:101]
	v_rcp_f32_e32 v246, v246
	v_rcp_f32_e32 v247, v247
	v_rcp_f32_e32 v248, v248
	v_rcp_f32_e32 v249, v249
	v_pk_mul_f32 v[120:121], v[120:121], v[246:247]
	v_pk_mul_f32 v[122:123], v[122:123], v[248:249]
	v_pk_mul_f32 v[120:121], v[120:121], v[112:113]
	v_pk_mul_f32 v[122:123], v[122:123], v[114:115]
	v_cvt_pk_bf16_f32 v112, v124, v125
	v_cvt_pk_bf16_f32 v113, v126, v127
	v_cvt_pk_bf16_f32 v114, v120, v121
	v_cvt_pk_bf16_f32 v115, v122, v123
	global_store_dwordx4 v[168:169], v[112:115], off
	v_pk_mul_f32 v[108:109], v[160:161], v[108:109] op_sel_hi:[0,1]
	v_pk_mul_f32 v[100:101], v[160:161], v[100:101] op_sel_hi:[0,1]
	v_pk_mul_f32 v[110:111], v[160:161], v[110:111] op_sel_hi:[0,1]
	v_pk_mul_f32 v[102:103], v[160:161], v[102:103] op_sel_hi:[0,1]
	v_pk_mul_f32 v[246:247], v[108:109], s[98:99]
	v_pk_mul_f32 v[248:249], v[110:111], s[98:99]
	v_exp_f32_e32 v246, v246
	v_exp_f32_e32 v247, v247
	v_exp_f32_e32 v248, v248
	v_exp_f32_e32 v249, v249
	v_pk_add_f32 v[246:247], v[246:247], s[100:101]
	v_pk_add_f32 v[248:249], v[248:249], s[100:101]
	v_rcp_f32_e32 v246, v246
	v_rcp_f32_e32 v247, v247
	v_rcp_f32_e32 v248, v248
	v_rcp_f32_e32 v249, v249
	v_pk_mul_f32 v[108:109], v[108:109], v[246:247]
	v_pk_mul_f32 v[110:111], v[110:111], v[248:249]
	v_pk_mul_f32 v[108:109], v[108:109], v[100:101]
	v_pk_mul_f32 v[110:111], v[110:111], v[102:103]
	v_or_b32_e32 v112, 16, v161
	v_mad_i64_i32 v[112:113], s[10:11], v112, s61, v[164:165]
	v_lshl_add_u64 v[112:113], v[112:113], 0, v[166:167]
	v_pk_mul_f32 v[104:105], v[160:161], v[104:105] op_sel_hi:[0,1]
	v_pk_mul_f32 v[96:97], v[160:161], v[96:97] op_sel_hi:[0,1]
	v_pk_mul_f32 v[106:107], v[160:161], v[106:107] op_sel_hi:[0,1]
	v_pk_mul_f32 v[98:99], v[160:161], v[98:99] op_sel_hi:[0,1]
	v_pk_mul_f32 v[246:247], v[104:105], s[98:99]
	v_pk_mul_f32 v[248:249], v[106:107], s[98:99]
	v_exp_f32_e32 v246, v246
	v_exp_f32_e32 v247, v247
	v_exp_f32_e32 v248, v248
	v_exp_f32_e32 v249, v249
	v_pk_add_f32 v[246:247], v[246:247], s[100:101]
	v_pk_add_f32 v[248:249], v[248:249], s[100:101]
	v_rcp_f32_e32 v246, v246
	v_rcp_f32_e32 v247, v247
	v_rcp_f32_e32 v248, v248
	v_rcp_f32_e32 v249, v249
	v_pk_mul_f32 v[104:105], v[104:105], v[246:247]
	v_pk_mul_f32 v[106:107], v[106:107], v[248:249]
	v_pk_mul_f32 v[104:105], v[104:105], v[96:97]
	v_pk_mul_f32 v[106:107], v[106:107], v[98:99]
	v_cvt_pk_bf16_f32 v96, v108, v109
	v_cvt_pk_bf16_f32 v97, v110, v111
	v_cvt_pk_bf16_f32 v98, v104, v105
	v_cvt_pk_bf16_f32 v99, v106, v107
	global_store_dwordx4 v[112:113], v[96:99], off
	v_pk_mul_f32 v[92:93], v[158:159], v[92:93] op_sel_hi:[0,1]
	v_pk_mul_f32 v[84:85], v[158:159], v[84:85] op_sel_hi:[0,1]
	v_pk_mul_f32 v[94:95], v[158:159], v[94:95] op_sel_hi:[0,1]
	v_pk_mul_f32 v[86:87], v[158:159], v[86:87] op_sel_hi:[0,1]
	v_pk_mul_f32 v[246:247], v[92:93], s[98:99]
	v_pk_mul_f32 v[248:249], v[94:95], s[98:99]
	v_exp_f32_e32 v246, v246
	v_exp_f32_e32 v247, v247
	v_exp_f32_e32 v248, v248
	v_exp_f32_e32 v249, v249
	v_pk_add_f32 v[246:247], v[246:247], s[100:101]
	v_pk_add_f32 v[248:249], v[248:249], s[100:101]
	v_rcp_f32_e32 v246, v246
	v_rcp_f32_e32 v247, v247
	v_rcp_f32_e32 v248, v248
	v_rcp_f32_e32 v249, v249
	v_pk_mul_f32 v[92:93], v[92:93], v[246:247]
	v_pk_mul_f32 v[94:95], v[94:95], v[248:249]
	v_pk_mul_f32 v[92:93], v[92:93], v[84:85]
	v_pk_mul_f32 v[94:95], v[94:95], v[86:87]
	v_or_b32_e32 v96, 32, v161
	v_mad_i64_i32 v[96:97], s[10:11], v96, s61, v[164:165]
	v_lshl_add_u64 v[96:97], v[96:97], 0, v[166:167]
	v_pk_mul_f32 v[88:89], v[158:159], v[88:89] op_sel_hi:[0,1]
	v_pk_mul_f32 v[80:81], v[158:159], v[80:81] op_sel_hi:[0,1]
	v_pk_mul_f32 v[90:91], v[158:159], v[90:91] op_sel_hi:[0,1]
	v_pk_mul_f32 v[82:83], v[158:159], v[82:83] op_sel_hi:[0,1]
	v_pk_mul_f32 v[246:247], v[88:89], s[98:99]
	v_pk_mul_f32 v[248:249], v[90:91], s[98:99]
; __device__ __forceinline__ unsigned cvt_pk_bf16(float lo, float hi) { unsigned r; asm volatile("v_cvt_pk_bf16_f32 %0, %1, %2" : "=v"(r) : "v"(lo), "v"(hi)); return r; }
;     __device__ __forceinline__ void operator()(const f32x4 (&acc)[2][2][4][2], const Unit& u, int wr, int wc, int fr, int fq, const float (&rv)[8]) const {
;     ...
;             for (int m = 0; m < 4; ++m) {
;                 bf16_t* rowp = O + (size_t)(row0 + ai * HALF + m * 16) * ldc + col0;
;                 const float r = rv[ai * 4 + m];
;                 const f32x4 g0 = acc[ai][0][m][0] * r, g1 = acc[ai][0][m][1] * r, u0 = acc[ai][1][m][0] * r, u1 = acc[ai][1][m][1] * r;
;                 u32x4 w;
;                 w.x = cvt_pk_bf16(silu_mul(g0[0], u0[0]), silu_mul(g0[1], u0[1]));
;                 w.y = cvt_pk_bf16(silu_mul(g0[2], u0[2]), silu_mul(g0[3], u0[3]));
;                 w.z = cvt_pk_bf16(silu_mul(g1[0], u1[0]), silu_mul(g1[1], u1[1]));
;                 w.w = cvt_pk_bf16(silu_mul(g1[2], u1[2]), silu_mul(g1[3], u1[3]));
;                 *(u32x4*)rowp = w;
	v_exp_f32_e32 v246, v246
	v_exp_f32_e32 v247, v247
	v_exp_f32_e32 v248, v248
	v_exp_f32_e32 v249, v249
	v_pk_add_f32 v[246:247], v[246:247], s[100:101]
	v_pk_add_f32 v[248:249], v[248:249], s[100:101]
	v_rcp_f32_e32 v246, v246
	v_rcp_f32_e32 v247, v247
	v_rcp_f32_e32 v248, v248
	v_rcp_f32_e32 v249, v249
	v_pk_mul_f32 v[88:89], v[88:89], v[246:247]
	v_pk_mul_f32 v[90:91], v[90:91], v[248:249]
	v_pk_mul_f32 v[88:89], v[88:89], v[80:81]
	v_pk_mul_f32 v[90:91], v[90:91], v[82:83]
	v_cvt_pk_bf16_f32 v80, v92, v93
	v_cvt_pk_bf16_f32 v81, v94, v95
	v_cvt_pk_bf16_f32 v82, v88, v89
	v_cvt_pk_bf16_f32 v83, v90, v91
	global_store_dwordx4 v[96:97], v[80:83], off
	v_pk_mul_f32 v[76:77], v[156:157], v[76:77] op_sel_hi:[0,1]
	v_pk_mul_f32 v[68:69], v[156:157], v[68:69] op_sel_hi:[0,1]
	v_pk_mul_f32 v[78:79], v[156:157], v[78:79] op_sel_hi:[0,1]
	v_pk_mul_f32 v[70:71], v[156:157], v[70:71] op_sel_hi:[0,1]
	v_pk_mul_f32 v[246:247], v[76:77], s[98:99]
	v_pk_mul_f32 v[248:249], v[78:79], s[98:99]
	v_exp_f32_e32 v246, v246
	v_exp_f32_e32 v247, v247
	v_exp_f32_e32 v248, v248
	v_exp_f32_e32 v249, v249
	v_pk_add_f32 v[246:247], v[246:247], s[100:101]
	v_pk_add_f32 v[248:249], v[248:249], s[100:101]
	v_rcp_f32_e32 v246, v246
	v_rcp_f32_e32 v247, v247
	v_rcp_f32_e32 v248, v248
	v_rcp_f32_e32 v249, v249
	v_pk_mul_f32 v[76:77], v[76:77], v[246:247]
	v_pk_mul_f32 v[78:79], v[78:79], v[248:249]
	v_pk_mul_f32 v[76:77], v[76:77], v[68:69]
	v_pk_mul_f32 v[78:79], v[78:79], v[70:71]
	v_or_b32_e32 v80, 48, v161
	v_mad_i64_i32 v[80:81], s[10:11], v80, s61, v[164:165]
	v_lshl_add_u64 v[80:81], v[80:81], 0, v[166:167]
	v_pk_mul_f32 v[72:73], v[156:157], v[72:73] op_sel_hi:[0,1]
	v_pk_mul_f32 v[64:65], v[156:157], v[64:65] op_sel_hi:[0,1]
	v_pk_mul_f32 v[74:75], v[156:157], v[74:75] op_sel_hi:[0,1]
	v_pk_mul_f32 v[66:67], v[156:157], v[66:67] op_sel_hi:[0,1]
	v_pk_mul_f32 v[246:247], v[72:73], s[98:99]
	v_pk_mul_f32 v[248:249], v[74:75], s[98:99]
	v_exp_f32_e32 v246, v246
	v_exp_f32_e32 v247, v247
	v_exp_f32_e32 v248, v248
	v_exp_f32_e32 v249, v249
	v_pk_add_f32 v[246:247], v[246:247], s[100:101]
	v_pk_add_f32 v[248:249], v[248:249], s[100:101]
	v_rcp_f32_e32 v246, v246
	v_rcp_f32_e32 v247, v247
	v_rcp_f32_e32 v248, v248
	v_rcp_f32_e32 v249, v249
	v_pk_mul_f32 v[72:73], v[72:73], v[246:247]
	v_pk_mul_f32 v[74:75], v[74:75], v[248:249]
	v_pk_mul_f32 v[72:73], v[72:73], v[64:65]
	v_pk_mul_f32 v[74:75], v[74:75], v[66:67]
	v_cvt_pk_bf16_f32 v64, v76, v77
	v_cvt_pk_bf16_f32 v65, v78, v79
	v_cvt_pk_bf16_f32 v66, v72, v73
	v_cvt_pk_bf16_f32 v67, v74, v75
	global_store_dwordx4 v[80:81], v[64:67], off
	v_pk_mul_f32 v[60:61], v[154:155], v[60:61] op_sel_hi:[0,1]
	v_pk_mul_f32 v[52:53], v[154:155], v[52:53] op_sel_hi:[0,1]
	v_pk_mul_f32 v[62:63], v[154:155], v[62:63] op_sel_hi:[0,1]
	v_pk_mul_f32 v[54:55], v[154:155], v[54:55] op_sel_hi:[0,1]
	v_pk_mul_f32 v[246:247], v[60:61], s[98:99]
	v_pk_mul_f32 v[248:249], v[62:63], s[98:99]
	v_exp_f32_e32 v246, v246
	v_exp_f32_e32 v247, v247
	v_exp_f32_e32 v248, v248
	v_exp_f32_e32 v249, v249
	v_pk_add_f32 v[246:247], v[246:247], s[100:101]
	v_pk_add_f32 v[248:249], v[248:249], s[100:101]
	v_rcp_f32_e32 v246, v246
	v_rcp_f32_e32 v247, v247
	v_rcp_f32_e32 v248, v248
	v_rcp_f32_e32 v249, v249
	v_pk_mul_f32 v[60:61], v[60:61], v[246:247]
	v_pk_mul_f32 v[62:63], v[62:63], v[248:249]
	v_pk_mul_f32 v[60:61], v[60:61], v[52:53]
	v_pk_mul_f32 v[62:63], v[62:63], v[54:55]
	v_add_u32_e32 v64, 0x80, v161
	v_mad_i64_i32 v[64:65], s[10:11], v64, s61, v[164:165]
	v_lshl_add_u64 v[64:65], v[64:65], 0, v[166:167]
	v_pk_mul_f32 v[56:57], v[154:155], v[56:57] op_sel_hi:[0,1]
	v_pk_mul_f32 v[48:49], v[154:155], v[48:49] op_sel_hi:[0,1]
	v_pk_mul_f32 v[58:59], v[154:155], v[58:59] op_sel_hi:[0,1]
	v_pk_mul_f32 v[50:51], v[154:155], v[50:51] op_sel_hi:[0,1]
	v_pk_mul_f32 v[246:247], v[56:57], s[98:99]
	v_pk_mul_f32 v[248:249], v[58:59], s[98:99]
	v_exp_f32_e32 v246, v246
	v_exp_f32_e32 v247, v247
	v_exp_f32_e32 v248, v248
	v_exp_f32_e32 v249, v249
	v_pk_add_f32 v[246:247], v[246:247], s[100:101]
	v_pk_add_f32 v[248:249], v[248:249], s[100:101]
	v_rcp_f32_e32 v246, v246
	v_rcp_f32_e32 v247, v247
	v_rcp_f32_e32 v248, v248
	v_rcp_f32_e32 v249, v249
	v_pk_mul_f32 v[56:57], v[56:57], v[246:247]
	v_pk_mul_f32 v[58:59], v[58:59], v[248:249]
	v_pk_mul_f32 v[56:57], v[56:57], v[48:49]
	v_pk_mul_f32 v[58:59], v[58:59], v[50:51]
	v_cvt_pk_bf16_f32 v48, v60, v61
	v_cvt_pk_bf16_f32 v49, v62, v63
	v_cvt_pk_bf16_f32 v50, v56, v57
	v_cvt_pk_bf16_f32 v51, v58, v59
	global_store_dwordx4 v[64:65], v[48:51], off
	v_pk_mul_f32 v[44:45], v[152:153], v[44:45] op_sel_hi:[0,1]
	v_pk_mul_f32 v[36:37], v[152:153], v[36:37] op_sel_hi:[0,1]
	v_pk_mul_f32 v[46:47], v[152:153], v[46:47] op_sel_hi:[0,1]
	v_pk_mul_f32 v[38:39], v[152:153], v[38:39] op_sel_hi:[0,1]
	v_pk_mul_f32 v[246:247], v[44:45], s[98:99]
	v_pk_mul_f32 v[248:249], v[46:47], s[98:99]
	v_exp_f32_e32 v246, v246
	v_exp_f32_e32 v247, v247
	v_exp_f32_e32 v248, v248
	v_exp_f32_e32 v249, v249
	v_pk_add_f32 v[246:247], v[246:247], s[100:101]
	v_pk_add_f32 v[248:249], v[248:249], s[100:101]
	v_rcp_f32_e32 v246, v246
	v_rcp_f32_e32 v247, v247
	v_rcp_f32_e32 v248, v248
	v_rcp_f32_e32 v249, v249
	v_pk_mul_f32 v[44:45], v[44:45], v[246:247]
	v_pk_mul_f32 v[46:47], v[46:47], v[248:249]
	v_pk_mul_f32 v[44:45], v[44:45], v[36:37]
	v_pk_mul_f32 v[46:47], v[46:47], v[38:39]
	v_add_u32_e32 v48, 0x90, v161
	v_mad_i64_i32 v[48:49], s[10:11], v48, s61, v[164:165]
	v_lshl_add_u64 v[48:49], v[48:49], 0, v[166:167]
; __device__ __forceinline__ unsigned cvt_pk_bf16(float lo, float hi) { unsigned r; asm volatile("v_cvt_pk_bf16_f32 %0, %1, %2" : "=v"(r) : "v"(lo), "v"(hi)); return r; }
; #define PG8_BAR __builtin_amdgcn_s_barrier()
;     __device__ __forceinline__ void operator()(const f32x4 (&acc)[2][2][4][2], const Unit& u, int wr, int wc, int fr, int fq, const float (&rv)[8]) const {
;     ...
;             for (int m = 0; m < 4; ++m) {
;                 bf16_t* rowp = O + (size_t)(row0 + ai * HALF + m * 16) * ldc + col0;
;                 const float r = rv[ai * 4 + m];
;                 const f32x4 g0 = acc[ai][0][m][0] * r, g1 = acc[ai][0][m][1] * r, u0 = acc[ai][1][m][0] * r, u1 = acc[ai][1][m][1] * r;
;                 u32x4 w;
;                 w.x = cvt_pk_bf16(silu_mul(g0[0], u0[0]), silu_mul(g0[1], u0[1]));
;                 w.y = cvt_pk_bf16(silu_mul(g0[2], u0[2]), silu_mul(g0[3], u0[3]));
;                 w.z = cvt_pk_bf16(silu_mul(g1[0], u1[0]), silu_mul(g1[1], u1[1]));
;                 w.w = cvt_pk_bf16(silu_mul(g1[2], u1[2]), silu_mul(g1[3], u1[3]));
;                 *(u32x4*)rowp = w;
; template <class Epi, class Sched, bool ALIGN_EPI = false, bool SP2 = false>
; __device__ __forceinline__ void gemm_phase(PG8_LAS unsigned char* lds, const Gemm g, const Sched& S, const Epi& E) {
;     ...
;         cur = nxt; cA = nA; cB = nB; ++ui;
;         E.pre(cur, wr, fr, epre);
;         if constexpr (ALIGN_EPI) { if (wr == 1) PG8_BAR; }
	v_pk_mul_f32 v[40:41], v[152:153], v[40:41] op_sel_hi:[0,1]
	v_pk_mul_f32 v[32:33], v[152:153], v[32:33] op_sel_hi:[0,1]
	v_pk_mul_f32 v[42:43], v[152:153], v[42:43] op_sel_hi:[0,1]
	v_pk_mul_f32 v[34:35], v[152:153], v[34:35] op_sel_hi:[0,1]
	v_pk_mul_f32 v[246:247], v[40:41], s[98:99]
	v_pk_mul_f32 v[248:249], v[42:43], s[98:99]
	v_exp_f32_e32 v246, v246
	v_exp_f32_e32 v247, v247
	v_exp_f32_e32 v248, v248
	v_exp_f32_e32 v249, v249
	v_pk_add_f32 v[246:247], v[246:247], s[100:101]
	v_pk_add_f32 v[248:249], v[248:249], s[100:101]
	v_rcp_f32_e32 v246, v246
	v_rcp_f32_e32 v247, v247
	v_rcp_f32_e32 v248, v248
	v_rcp_f32_e32 v249, v249
	v_pk_mul_f32 v[40:41], v[40:41], v[246:247]
	v_pk_mul_f32 v[42:43], v[42:43], v[248:249]
	v_pk_mul_f32 v[40:41], v[40:41], v[32:33]
	v_pk_mul_f32 v[42:43], v[42:43], v[34:35]
	v_cvt_pk_bf16_f32 v32, v44, v45
	v_cvt_pk_bf16_f32 v33, v46, v47
	v_cvt_pk_bf16_f32 v34, v40, v41
	v_cvt_pk_bf16_f32 v35, v42, v43
	global_store_dwordx4 v[48:49], v[32:35], off
	v_pk_mul_f32 v[28:29], v[146:147], v[28:29] op_sel_hi:[0,1]
	v_pk_mul_f32 v[20:21], v[146:147], v[20:21] op_sel_hi:[0,1]
	v_pk_mul_f32 v[30:31], v[146:147], v[30:31] op_sel_hi:[0,1]
	v_pk_mul_f32 v[22:23], v[146:147], v[22:23] op_sel_hi:[0,1]
	v_pk_mul_f32 v[246:247], v[28:29], s[98:99]
	v_pk_mul_f32 v[248:249], v[30:31], s[98:99]
	v_exp_f32_e32 v246, v246
	v_exp_f32_e32 v247, v247
	v_exp_f32_e32 v248, v248
	v_exp_f32_e32 v249, v249
	v_pk_add_f32 v[246:247], v[246:247], s[100:101]
	v_pk_add_f32 v[248:249], v[248:249], s[100:101]
	v_rcp_f32_e32 v246, v246
	v_rcp_f32_e32 v247, v247
	v_rcp_f32_e32 v248, v248
	v_rcp_f32_e32 v249, v249
	v_pk_mul_f32 v[28:29], v[28:29], v[246:247]
	v_pk_mul_f32 v[30:31], v[30:31], v[248:249]
	v_pk_mul_f32 v[28:29], v[28:29], v[20:21]
	v_pk_mul_f32 v[30:31], v[30:31], v[22:23]
	v_add_u32_e32 v32, 0xa0, v161
	v_mad_i64_i32 v[32:33], s[10:11], v32, s61, v[164:165]
	v_lshl_add_u64 v[32:33], v[32:33], 0, v[166:167]
	v_pk_mul_f32 v[24:25], v[146:147], v[24:25] op_sel_hi:[0,1]
	v_pk_mul_f32 v[16:17], v[146:147], v[16:17] op_sel_hi:[0,1]
	v_pk_mul_f32 v[26:27], v[146:147], v[26:27] op_sel_hi:[0,1]
	v_pk_mul_f32 v[18:19], v[146:147], v[18:19] op_sel_hi:[0,1]
	v_pk_mul_f32 v[246:247], v[24:25], s[98:99]
	v_pk_mul_f32 v[248:249], v[26:27], s[98:99]
	v_exp_f32_e32 v246, v246
	v_exp_f32_e32 v247, v247
	v_exp_f32_e32 v248, v248
	v_exp_f32_e32 v249, v249
	v_pk_add_f32 v[246:247], v[246:247], s[100:101]
	v_pk_add_f32 v[248:249], v[248:249], s[100:101]
	v_rcp_f32_e32 v246, v246
	v_rcp_f32_e32 v247, v247
	v_rcp_f32_e32 v248, v248
	v_rcp_f32_e32 v249, v249
	v_pk_mul_f32 v[24:25], v[24:25], v[246:247]
	v_pk_mul_f32 v[26:27], v[26:27], v[248:249]
	v_pk_mul_f32 v[24:25], v[24:25], v[16:17]
	v_pk_mul_f32 v[26:27], v[26:27], v[18:19]
	v_cvt_pk_bf16_f32 v16, v28, v29
	v_cvt_pk_bf16_f32 v17, v30, v31
	v_cvt_pk_bf16_f32 v18, v24, v25
	v_cvt_pk_bf16_f32 v19, v26, v27
	global_store_dwordx4 v[32:33], v[16:19], off
	v_pk_mul_f32 v[12:13], v[136:137], v[12:13] op_sel_hi:[0,1]
	v_pk_mul_f32 v[4:5], v[136:137], v[4:5] op_sel_hi:[0,1]
	v_pk_mul_f32 v[14:15], v[136:137], v[14:15] op_sel_hi:[0,1]
	v_pk_mul_f32 v[6:7], v[136:137], v[6:7] op_sel_hi:[0,1]
	v_pk_mul_f32 v[246:247], v[12:13], s[98:99]
	v_pk_mul_f32 v[248:249], v[14:15], s[98:99]
	v_exp_f32_e32 v246, v246
	v_exp_f32_e32 v247, v247
	v_exp_f32_e32 v248, v248
	v_exp_f32_e32 v249, v249
	v_pk_add_f32 v[246:247], v[246:247], s[100:101]
	v_pk_add_f32 v[248:249], v[248:249], s[100:101]
	v_rcp_f32_e32 v246, v246
	v_rcp_f32_e32 v247, v247
	v_rcp_f32_e32 v248, v248
	v_rcp_f32_e32 v249, v249
	v_pk_mul_f32 v[12:13], v[12:13], v[246:247]
	v_pk_mul_f32 v[14:15], v[14:15], v[248:249]
	v_pk_mul_f32 v[12:13], v[12:13], v[4:5]
	v_pk_mul_f32 v[14:15], v[14:15], v[6:7]
	v_add_u32_e32 v16, 0xb0, v161
	v_mad_i64_i32 v[16:17], s[10:11], v16, s61, v[164:165]
	v_lshl_add_u64 v[16:17], v[16:17], 0, v[166:167]
	s_andn2_b64 vcc, exec, s[0:1]
	s_mov_b64 s[0:1], -1
	v_pk_mul_f32 v[8:9], v[136:137], v[8:9] op_sel_hi:[0,1]
	v_pk_mul_f32 v[0:1], v[136:137], v[0:1] op_sel_hi:[0,1]
	v_pk_mul_f32 v[10:11], v[136:137], v[10:11] op_sel_hi:[0,1]
	v_pk_mul_f32 v[2:3], v[136:137], v[2:3] op_sel_hi:[0,1]
	v_pk_mul_f32 v[246:247], v[8:9], s[98:99]
	v_pk_mul_f32 v[248:249], v[10:11], s[98:99]
	v_exp_f32_e32 v246, v246
	v_exp_f32_e32 v247, v247
	v_exp_f32_e32 v248, v248
	v_exp_f32_e32 v249, v249
	v_pk_add_f32 v[246:247], v[246:247], s[100:101]
	v_pk_add_f32 v[248:249], v[248:249], s[100:101]
	v_rcp_f32_e32 v246, v246
	v_rcp_f32_e32 v247, v247
	v_rcp_f32_e32 v248, v248
	v_rcp_f32_e32 v249, v249
	v_pk_mul_f32 v[8:9], v[8:9], v[246:247]
	v_pk_mul_f32 v[10:11], v[10:11], v[248:249]
	v_pk_mul_f32 v[8:9], v[8:9], v[0:1]
	v_pk_mul_f32 v[10:11], v[10:11], v[2:3]
	v_cvt_pk_bf16_f32 v0, v12, v13
	v_cvt_pk_bf16_f32 v1, v14, v15
	v_cvt_pk_bf16_f32 v2, v8, v9
	v_cvt_pk_bf16_f32 v3, v10, v11
	global_store_dwordx4 v[16:17], v[0:3], off
	s_cbranch_vccnz .LBB0_696
	s_nop 0
	v_lshl_add_u32 v0, s36, 8, v137
	v_ashrrev_i32_e32 v1, 31, v0
	v_lshl_add_u64 v[0:1], v[0:1], 2, s[16:17]
	global_load_dword v162, v[0:1], off
	global_load_dword v160, v[0:1], off offset:64
	global_load_dword v158, v[0:1], off offset:128
	global_load_dword v156, v[0:1], off offset:192
	global_load_dword v154, v[0:1], off offset:512
	global_load_dword v152, v[0:1], off offset:576
	global_load_dword v146, v[0:1], off offset:640
	global_load_dword v136, v[0:1], off offset:704
	s_andn2_b64 vcc, exec, s[4:5]
	s_cbranch_vccnz .LBB0_695
	s_barrier
	s_branch .LBB0_695
